# P1 E-matrix table and P3 carry-matrix table loops unrolled with their loads issued ahead of the previous item's store
# speedup vs baseline: 1.0119x; 1.0042x over previous
; DI unsigned pk2(float lo, float hi) { f32x2_t v = {lo, hi}; bf16x2_t b = __builtin_convertvector(v, bf16x2_t); return __builtin_bit_cast(unsigned, b); }
; DI void phase1(const Params& p, unsigned char* smem) {
;     ...
;     for (int idx = gtid; idx < 32 * 128 * 128; idx += gstr) {
;         const int g = idx >> 14, m = (idx >> 7) & 127, k8 = idx & 127;
;         const int pp = m & 63, j = k8 >> 1, c20 = (k8 & 1) * 8;
;         const float2 a = apow[((size_t)g * 65 + (63 - j)) * 64 + pp];
;         const float4* bp = (const float4*)(bbar + (size_t)(g * 64 + pp) * 16 + c20);
;         float o[8];
; #pragma unroll
;         for (int e = 0; e < 4; ++e) {
;             float4 b2 = bp[e];
;             o[2 * e] = (m < 64) ? (a.x * b2.x - a.y * b2.y) : (a.x * b2.y + a.y * b2.x);
;             o[2 * e + 1] = (m < 64) ? (a.x * b2.z - a.y * b2.w) : (a.x * b2.w + a.y * b2.z);
;         }
;         *(uint4*)(emat + (size_t)idx * 8) = make_uint4(pk2(o[0], o[1]), pk2(o[2], o[3]), pk2(o[4], o[5]), pk2(o[6], o[7]));
.LBB0_221:
	v_ashrrev_i32_e32 v7, 14, v0
	v_bfe_u32 v10, v0, 7, 6
	v_not_b32_e32 v4, v0
	v_mul_i32_i24_e32 v6, 0x41, v7
	v_bfe_u32 v4, v4, 1, 6
	v_lshl_or_b32 v8, v7, 6, v10
	v_ashrrev_i32_e32 v7, 31, v6
	v_lshl_add_u64 v[6:7], v[4:5], 0, v[6:7]
	v_ashrrev_i32_e32 v9, 31, v8
	v_lshlrev_b64 v[6:7], 9, v[6:7]
	v_and_b32_e32 v11, 8, v1
	v_lshlrev_b32_e32 v4, 3, v10
	v_lshlrev_b64 v[8:9], 7, v[8:9]
	v_lshl_add_u64 v[6:7], s[4:5], 0, v[6:7]
	v_lshl_add_u64 v[8:9], s[6:7], 0, v[8:9]
	v_lshl_add_u64 v[22:23], v[6:7], 0, v[4:5]
	v_lshlrev_b32_e32 v4, 3, v11
	v_lshl_add_u64 v[18:19], v[8:9], 0, v[4:5]
	global_load_dwordx4 v[128:131], v[18:19], off
	global_load_dwordx4 v[132:135], v[18:19], off offset:16
	global_load_dwordx4 v[136:139], v[18:19], off offset:32
	s_nop 0
	global_load_dwordx4 v[140:143], v[18:19], off offset:48
	s_nop 0
	global_load_dwordx2 v[144:145], v[22:23], off
	v_and_b32_e32 v200, 0x2000, v0
	v_add_u32_e32 v0, s8, v0
	v_add_u32_e32 v1, s3, v1
	v_ashrrev_i32_e32 v7, 14, v0
	v_bfe_u32 v10, v0, 7, 6
	v_not_b32_e32 v4, v0
	v_mul_i32_i24_e32 v6, 0x41, v7
	v_bfe_u32 v4, v4, 1, 6
	v_lshl_or_b32 v8, v7, 6, v10
	v_ashrrev_i32_e32 v7, 31, v6
	v_lshl_add_u64 v[6:7], v[4:5], 0, v[6:7]
	v_ashrrev_i32_e32 v9, 31, v8
	v_lshlrev_b64 v[6:7], 9, v[6:7]
	v_and_b32_e32 v11, 8, v1
	v_lshlrev_b32_e32 v4, 3, v10
	v_lshlrev_b64 v[8:9], 7, v[8:9]
	v_lshl_add_u64 v[6:7], s[4:5], 0, v[6:7]
	v_lshl_add_u64 v[8:9], s[6:7], 0, v[8:9]
	v_lshl_add_u64 v[22:23], v[6:7], 0, v[4:5]
	v_lshlrev_b32_e32 v4, 3, v11
	v_lshl_add_u64 v[18:19], v[8:9], 0, v[4:5]
	global_load_dwordx4 v[146:149], v[18:19], off
	global_load_dwordx4 v[150:153], v[18:19], off offset:16
	global_load_dwordx4 v[154:157], v[18:19], off offset:32
	s_nop 0
	global_load_dwordx4 v[158:161], v[18:19], off offset:48
	s_nop 0
	global_load_dwordx2 v[162:163], v[22:23], off
	v_and_b32_e32 v201, 0x2000, v0
	v_add_u32_e32 v0, s8, v0
	v_add_u32_e32 v1, s3, v1
	v_ashrrev_i32_e32 v7, 14, v0
	v_bfe_u32 v10, v0, 7, 6
	v_not_b32_e32 v4, v0
	v_mul_i32_i24_e32 v6, 0x41, v7
	v_bfe_u32 v4, v4, 1, 6
	v_lshl_or_b32 v8, v7, 6, v10
	v_ashrrev_i32_e32 v7, 31, v6
	v_lshl_add_u64 v[6:7], v[4:5], 0, v[6:7]
	v_ashrrev_i32_e32 v9, 31, v8
	v_lshlrev_b64 v[6:7], 9, v[6:7]
	v_and_b32_e32 v11, 8, v1
	v_lshlrev_b32_e32 v4, 3, v10
	v_lshlrev_b64 v[8:9], 7, v[8:9]
	v_lshl_add_u64 v[6:7], s[4:5], 0, v[6:7]
	v_lshl_add_u64 v[8:9], s[6:7], 0, v[8:9]
	v_lshl_add_u64 v[22:23], v[6:7], 0, v[4:5]
	v_lshlrev_b32_e32 v4, 3, v11
	v_lshl_add_u64 v[18:19], v[8:9], 0, v[4:5]
	global_load_dwordx4 v[164:167], v[18:19], off
	global_load_dwordx4 v[168:171], v[18:19], off offset:16
	global_load_dwordx4 v[172:175], v[18:19], off offset:32
	s_nop 0
	global_load_dwordx4 v[176:179], v[18:19], off offset:48
	s_nop 0
	global_load_dwordx2 v[180:181], v[22:23], off
	v_and_b32_e32 v202, 0x2000, v0
	v_add_u32_e32 v0, s8, v0
	v_add_u32_e32 v1, s3, v1
	v_ashrrev_i32_e32 v7, 14, v0
	v_bfe_u32 v10, v0, 7, 6
	v_not_b32_e32 v4, v0
	v_mul_i32_i24_e32 v6, 0x41, v7
	v_bfe_u32 v4, v4, 1, 6
	v_lshl_or_b32 v8, v7, 6, v10
	v_ashrrev_i32_e32 v7, 31, v6
	v_lshl_add_u64 v[6:7], v[4:5], 0, v[6:7]
	v_ashrrev_i32_e32 v9, 31, v8
	v_lshlrev_b64 v[6:7], 9, v[6:7]
	v_and_b32_e32 v11, 8, v1
	v_lshlrev_b32_e32 v4, 3, v10
	v_lshlrev_b64 v[8:9], 7, v[8:9]
	v_lshl_add_u64 v[6:7], s[4:5], 0, v[6:7]
	v_lshl_add_u64 v[8:9], s[6:7], 0, v[8:9]
	v_lshl_add_u64 v[22:23], v[6:7], 0, v[4:5]
	v_lshlrev_b32_e32 v4, 3, v11
	v_lshl_add_u64 v[18:19], v[8:9], 0, v[4:5]
	global_load_dwordx4 v[182:185], v[18:19], off
	global_load_dwordx4 v[186:189], v[18:19], off offset:16
	global_load_dwordx4 v[190:193], v[18:19], off offset:32
	s_nop 0
	global_load_dwordx4 v[194:197], v[18:19], off offset:48
	s_nop 0
	global_load_dwordx2 v[198:199], v[22:23], off
	v_and_b32_e32 v203, 0x2000, v0
	v_add_u32_e32 v0, s8, v0
	v_add_u32_e32 v1, s3, v1
	s_waitcnt vmcnt(15)
	v_mov_b64_e32 v[6:7], v[128:129]
	v_mov_b64_e32 v[8:9], v[130:131]
	v_mov_b64_e32 v[10:11], v[132:133]
	v_mov_b64_e32 v[12:13], v[134:135]
	v_mov_b64_e32 v[14:15], v[136:137]
	v_mov_b64_e32 v[16:17], v[138:139]
	v_mov_b64_e32 v[18:19], v[140:141]
	v_mov_b64_e32 v[20:21], v[142:143]
	v_mov_b64_e32 v[22:23], v[144:145]
	v_cmp_eq_u32_e32 vcc, 0, v200
	s_nop 1
	v_mov_b32_e32 v24, v7
	v_mov_b32_e32 v25, v8
	v_mov_b32_e32 v26, v11
	v_mov_b32_e32 v27, v12
	v_mov_b32_e32 v28, v15
	v_mov_b32_e32 v29, v16
	v_mov_b32_e32 v31, v20
	v_mov_b32_e32 v33, v8
	v_mov_b32_e32 v8, v7
	v_mov_b32_e32 v34, v9
	v_mov_b32_e32 v35, v6
	v_mov_b32_e32 v7, v12
	v_mov_b32_e32 v12, v11
	v_mov_b32_e32 v36, v13
	v_mov_b32_e32 v37, v10
	v_mov_b32_e32 v11, v16
	v_mov_b32_e32 v16, v15
	v_mov_b32_e32 v38, v17
	v_mov_b32_e32 v39, v14
	v_mov_b32_e32 v15, v20
	v_mov_b32_e32 v20, v19
	v_mov_b32_e32 v40, v21
	v_mov_b32_e32 v41, v18
	v_mov_b32_e32 v30, v19
	v_mov_b32_e32 v32, v6
	v_mov_b32_e32 v6, v10
	v_mov_b32_e32 v10, v14
	v_mov_b32_e32 v14, v18
	v_pk_mul_f32 v[8:9], v[22:23], v[8:9] op_sel:[1,0]
	v_pk_mul_f32 v[18:19], v[22:23], v[34:35]
	v_pk_mul_f32 v[12:13], v[22:23], v[12:13] op_sel:[1,0]
	v_pk_mul_f32 v[34:35], v[22:23], v[36:37]
	v_pk_mul_f32 v[16:17], v[22:23], v[16:17] op_sel:[1,0]
	v_pk_mul_f32 v[36:37], v[22:23], v[38:39]
	v_pk_mul_f32 v[20:21], v[22:23], v[20:21] op_sel:[1,0]
	v_pk_mul_f32 v[38:39], v[22:23], v[40:41]
	v_pk_fma_f32 v[8:9], v[22:23], v[32:33], v[8:9] op_sel_hi:[0,1,1] neg_lo:[0,0,1] neg_hi:[0,0,1]
	v_pk_fma_f32 v[18:19], v[22:23], v[24:25], v[18:19] op_sel:[0,0,1] op_sel_hi:[1,1,0]
	v_pk_fma_f32 v[6:7], v[22:23], v[6:7], v[12:13] op_sel_hi:[0,1,1] neg_lo:[0,0,1] neg_hi:[0,0,1]
	v_pk_fma_f32 v[12:13], v[22:23], v[26:27], v[34:35] op_sel:[0,0,1] op_sel_hi:[1,1,0]
	v_pk_fma_f32 v[10:11], v[22:23], v[10:11], v[16:17] op_sel_hi:[0,1,1] neg_lo:[0,0,1] neg_hi:[0,0,1]
	v_pk_fma_f32 v[16:17], v[22:23], v[28:29], v[36:37] op_sel:[0,0,1] op_sel_hi:[1,1,0]
	v_pk_fma_f32 v[14:15], v[22:23], v[14:15], v[20:21] op_sel_hi:[0,1,1] neg_lo:[0,0,1] neg_hi:[0,0,1]
	v_pk_fma_f32 v[20:21], v[22:23], v[30:31], v[38:39] op_sel:[0,0,1] op_sel_hi:[1,1,0]
	v_cndmask_b32_e32 v4, v19, v9, vcc
	v_cndmask_b32_e32 v8, v18, v8, vcc
	v_cndmask_b32_e32 v7, v13, v7, vcc
	v_cndmask_b32_e32 v9, v12, v6, vcc
	v_cndmask_b32_e32 v11, v17, v11, vcc
	v_cndmask_b32_e32 v10, v16, v10, vcc
	v_cndmask_b32_e32 v12, v21, v15, vcc
	v_cndmask_b32_e32 v13, v20, v14, vcc
	v_cvt_pk_bf16_f32 v6, v8, v4
	v_cvt_pk_bf16_f32 v7, v9, v7
	v_cvt_pk_bf16_f32 v8, v10, v11
	v_cvt_pk_bf16_f32 v9, v13, v12
	global_store_dwordx4 v[2:3], v[6:9], off
	v_lshl_add_u64 v[2:3], v[2:3], 0, s[10:11]
	s_waitcnt vmcnt(11)
; DI unsigned pk2(float lo, float hi) { f32x2_t v = {lo, hi}; bf16x2_t b = __builtin_convertvector(v, bf16x2_t); return __builtin_bit_cast(unsigned, b); }
; DI void phase1(const Params& p, unsigned char* smem) {
;     ...
;         const int pp = m & 63, j = k8 >> 1, c20 = (k8 & 1) * 8;
;         const float2 a = apow[((size_t)g * 65 + (63 - j)) * 64 + pp];
;         const float4* bp = (const float4*)(bbar + (size_t)(g * 64 + pp) * 16 + c20);
;         float o[8];
; #pragma unroll
;         for (int e = 0; e < 4; ++e) {
;             float4 b2 = bp[e];
;             o[2 * e] = (m < 64) ? (a.x * b2.x - a.y * b2.y) : (a.x * b2.y + a.y * b2.x);
;             o[2 * e + 1] = (m < 64) ? (a.x * b2.z - a.y * b2.w) : (a.x * b2.w + a.y * b2.z);
;         }
;         *(uint4*)(emat + (size_t)idx * 8) = make_uint4(pk2(o[0], o[1]), pk2(o[2], o[3]), pk2(o[4], o[5]), pk2(o[6], o[7]));
	v_mov_b64_e32 v[6:7], v[146:147]
	v_mov_b64_e32 v[8:9], v[148:149]
	v_mov_b64_e32 v[10:11], v[150:151]
	v_mov_b64_e32 v[12:13], v[152:153]
	v_mov_b64_e32 v[14:15], v[154:155]
	v_mov_b64_e32 v[16:17], v[156:157]
	v_mov_b64_e32 v[18:19], v[158:159]
	v_mov_b64_e32 v[20:21], v[160:161]
	v_mov_b64_e32 v[22:23], v[162:163]
	v_cmp_eq_u32_e32 vcc, 0, v201
	s_nop 1
	v_mov_b32_e32 v24, v7
	v_mov_b32_e32 v25, v8
	v_mov_b32_e32 v26, v11
	v_mov_b32_e32 v27, v12
	v_mov_b32_e32 v28, v15
	v_mov_b32_e32 v29, v16
	v_mov_b32_e32 v31, v20
	v_mov_b32_e32 v33, v8
	v_mov_b32_e32 v8, v7
	v_mov_b32_e32 v34, v9
	v_mov_b32_e32 v35, v6
	v_mov_b32_e32 v7, v12
	v_mov_b32_e32 v12, v11
	v_mov_b32_e32 v36, v13
	v_mov_b32_e32 v37, v10
	v_mov_b32_e32 v11, v16
	v_mov_b32_e32 v16, v15
	v_mov_b32_e32 v38, v17
	v_mov_b32_e32 v39, v14
	v_mov_b32_e32 v15, v20
	v_mov_b32_e32 v20, v19
	v_mov_b32_e32 v40, v21
	v_mov_b32_e32 v41, v18
	v_mov_b32_e32 v30, v19
	v_mov_b32_e32 v32, v6
	v_mov_b32_e32 v6, v10
	v_mov_b32_e32 v10, v14
	v_mov_b32_e32 v14, v18
	v_pk_mul_f32 v[8:9], v[22:23], v[8:9] op_sel:[1,0]
	v_pk_mul_f32 v[18:19], v[22:23], v[34:35]
	v_pk_mul_f32 v[12:13], v[22:23], v[12:13] op_sel:[1,0]
	v_pk_mul_f32 v[34:35], v[22:23], v[36:37]
	v_pk_mul_f32 v[16:17], v[22:23], v[16:17] op_sel:[1,0]
	v_pk_mul_f32 v[36:37], v[22:23], v[38:39]
	v_pk_mul_f32 v[20:21], v[22:23], v[20:21] op_sel:[1,0]
	v_pk_mul_f32 v[38:39], v[22:23], v[40:41]
	v_pk_fma_f32 v[8:9], v[22:23], v[32:33], v[8:9] op_sel_hi:[0,1,1] neg_lo:[0,0,1] neg_hi:[0,0,1]
	v_pk_fma_f32 v[18:19], v[22:23], v[24:25], v[18:19] op_sel:[0,0,1] op_sel_hi:[1,1,0]
	v_pk_fma_f32 v[6:7], v[22:23], v[6:7], v[12:13] op_sel_hi:[0,1,1] neg_lo:[0,0,1] neg_hi:[0,0,1]
	v_pk_fma_f32 v[12:13], v[22:23], v[26:27], v[34:35] op_sel:[0,0,1] op_sel_hi:[1,1,0]
	v_pk_fma_f32 v[10:11], v[22:23], v[10:11], v[16:17] op_sel_hi:[0,1,1] neg_lo:[0,0,1] neg_hi:[0,0,1]
	v_pk_fma_f32 v[16:17], v[22:23], v[28:29], v[36:37] op_sel:[0,0,1] op_sel_hi:[1,1,0]
	v_pk_fma_f32 v[14:15], v[22:23], v[14:15], v[20:21] op_sel_hi:[0,1,1] neg_lo:[0,0,1] neg_hi:[0,0,1]
	v_pk_fma_f32 v[20:21], v[22:23], v[30:31], v[38:39] op_sel:[0,0,1] op_sel_hi:[1,1,0]
	v_cndmask_b32_e32 v4, v19, v9, vcc
	v_cndmask_b32_e32 v8, v18, v8, vcc
	v_cndmask_b32_e32 v7, v13, v7, vcc
	v_cndmask_b32_e32 v9, v12, v6, vcc
	v_cndmask_b32_e32 v11, v17, v11, vcc
	v_cndmask_b32_e32 v10, v16, v10, vcc
	v_cndmask_b32_e32 v12, v21, v15, vcc
	v_cndmask_b32_e32 v13, v20, v14, vcc
	v_cvt_pk_bf16_f32 v6, v8, v4
	v_cvt_pk_bf16_f32 v7, v9, v7
	v_cvt_pk_bf16_f32 v8, v10, v11
	v_cvt_pk_bf16_f32 v9, v13, v12
	global_store_dwordx4 v[2:3], v[6:9], off
	v_lshl_add_u64 v[2:3], v[2:3], 0, s[10:11]
	s_waitcnt vmcnt(7)
; DI unsigned pk2(float lo, float hi) { f32x2_t v = {lo, hi}; bf16x2_t b = __builtin_convertvector(v, bf16x2_t); return __builtin_bit_cast(unsigned, b); }
; DI void phase1(const Params& p, unsigned char* smem) {
;     ...
;         const int pp = m & 63, j = k8 >> 1, c20 = (k8 & 1) * 8;
;         const float2 a = apow[((size_t)g * 65 + (63 - j)) * 64 + pp];
;         const float4* bp = (const float4*)(bbar + (size_t)(g * 64 + pp) * 16 + c20);
;         float o[8];
; #pragma unroll
;         for (int e = 0; e < 4; ++e) {
;             float4 b2 = bp[e];
;             o[2 * e] = (m < 64) ? (a.x * b2.x - a.y * b2.y) : (a.x * b2.y + a.y * b2.x);
;             o[2 * e + 1] = (m < 64) ? (a.x * b2.z - a.y * b2.w) : (a.x * b2.w + a.y * b2.z);
;         }
;         *(uint4*)(emat + (size_t)idx * 8) = make_uint4(pk2(o[0], o[1]), pk2(o[2], o[3]), pk2(o[4], o[5]), pk2(o[6], o[7]));
	v_mov_b64_e32 v[6:7], v[164:165]
	v_mov_b64_e32 v[8:9], v[166:167]
	v_mov_b64_e32 v[10:11], v[168:169]
	v_mov_b64_e32 v[12:13], v[170:171]
	v_mov_b64_e32 v[14:15], v[172:173]
	v_mov_b64_e32 v[16:17], v[174:175]
	v_mov_b64_e32 v[18:19], v[176:177]
	v_mov_b64_e32 v[20:21], v[178:179]
	v_mov_b64_e32 v[22:23], v[180:181]
	v_cmp_eq_u32_e32 vcc, 0, v202
	s_nop 1
	v_mov_b32_e32 v24, v7
	v_mov_b32_e32 v25, v8
	v_mov_b32_e32 v26, v11
	v_mov_b32_e32 v27, v12
	v_mov_b32_e32 v28, v15
	v_mov_b32_e32 v29, v16
	v_mov_b32_e32 v31, v20
	v_mov_b32_e32 v33, v8
	v_mov_b32_e32 v8, v7
	v_mov_b32_e32 v34, v9
	v_mov_b32_e32 v35, v6
	v_mov_b32_e32 v7, v12
	v_mov_b32_e32 v12, v11
	v_mov_b32_e32 v36, v13
	v_mov_b32_e32 v37, v10
	v_mov_b32_e32 v11, v16
	v_mov_b32_e32 v16, v15
	v_mov_b32_e32 v38, v17
	v_mov_b32_e32 v39, v14
	v_mov_b32_e32 v15, v20
	v_mov_b32_e32 v20, v19
	v_mov_b32_e32 v40, v21
	v_mov_b32_e32 v41, v18
	v_mov_b32_e32 v30, v19
	v_mov_b32_e32 v32, v6
	v_mov_b32_e32 v6, v10
	v_mov_b32_e32 v10, v14
	v_mov_b32_e32 v14, v18
	v_pk_mul_f32 v[8:9], v[22:23], v[8:9] op_sel:[1,0]
	v_pk_mul_f32 v[18:19], v[22:23], v[34:35]
	v_pk_mul_f32 v[12:13], v[22:23], v[12:13] op_sel:[1,0]
	v_pk_mul_f32 v[34:35], v[22:23], v[36:37]
	v_pk_mul_f32 v[16:17], v[22:23], v[16:17] op_sel:[1,0]
	v_pk_mul_f32 v[36:37], v[22:23], v[38:39]
	v_pk_mul_f32 v[20:21], v[22:23], v[20:21] op_sel:[1,0]
	v_pk_mul_f32 v[38:39], v[22:23], v[40:41]
	v_pk_fma_f32 v[8:9], v[22:23], v[32:33], v[8:9] op_sel_hi:[0,1,1] neg_lo:[0,0,1] neg_hi:[0,0,1]
	v_pk_fma_f32 v[18:19], v[22:23], v[24:25], v[18:19] op_sel:[0,0,1] op_sel_hi:[1,1,0]
	v_pk_fma_f32 v[6:7], v[22:23], v[6:7], v[12:13] op_sel_hi:[0,1,1] neg_lo:[0,0,1] neg_hi:[0,0,1]
	v_pk_fma_f32 v[12:13], v[22:23], v[26:27], v[34:35] op_sel:[0,0,1] op_sel_hi:[1,1,0]
	v_pk_fma_f32 v[10:11], v[22:23], v[10:11], v[16:17] op_sel_hi:[0,1,1] neg_lo:[0,0,1] neg_hi:[0,0,1]
	v_pk_fma_f32 v[16:17], v[22:23], v[28:29], v[36:37] op_sel:[0,0,1] op_sel_hi:[1,1,0]
	v_pk_fma_f32 v[14:15], v[22:23], v[14:15], v[20:21] op_sel_hi:[0,1,1] neg_lo:[0,0,1] neg_hi:[0,0,1]
	v_pk_fma_f32 v[20:21], v[22:23], v[30:31], v[38:39] op_sel:[0,0,1] op_sel_hi:[1,1,0]
	v_cndmask_b32_e32 v4, v19, v9, vcc
	v_cndmask_b32_e32 v8, v18, v8, vcc
	v_cndmask_b32_e32 v7, v13, v7, vcc
	v_cndmask_b32_e32 v9, v12, v6, vcc
	v_cndmask_b32_e32 v11, v17, v11, vcc
	v_cndmask_b32_e32 v10, v16, v10, vcc
	v_cndmask_b32_e32 v12, v21, v15, vcc
	v_cndmask_b32_e32 v13, v20, v14, vcc
	v_cvt_pk_bf16_f32 v6, v8, v4
	v_cvt_pk_bf16_f32 v7, v9, v7
	v_cvt_pk_bf16_f32 v8, v10, v11
	v_cvt_pk_bf16_f32 v9, v13, v12
	global_store_dwordx4 v[2:3], v[6:9], off
	v_lshl_add_u64 v[2:3], v[2:3], 0, s[10:11]
	s_waitcnt vmcnt(3)
	v_mov_b64_e32 v[6:7], v[182:183]
	v_mov_b64_e32 v[8:9], v[184:185]
	v_mov_b64_e32 v[10:11], v[186:187]
	v_mov_b64_e32 v[12:13], v[188:189]
	v_mov_b64_e32 v[14:15], v[190:191]
	v_mov_b64_e32 v[16:17], v[192:193]
	v_mov_b64_e32 v[18:19], v[194:195]
	v_mov_b64_e32 v[20:21], v[196:197]
	v_mov_b64_e32 v[22:23], v[198:199]
	v_cmp_eq_u32_e32 vcc, 0, v203
	s_nop 1
	v_mov_b32_e32 v24, v7
	v_mov_b32_e32 v25, v8
	v_mov_b32_e32 v26, v11
	v_mov_b32_e32 v27, v12
	v_mov_b32_e32 v28, v15
	v_mov_b32_e32 v29, v16
	v_mov_b32_e32 v31, v20
	v_mov_b32_e32 v33, v8
	v_mov_b32_e32 v8, v7
	v_mov_b32_e32 v34, v9
	v_mov_b32_e32 v35, v6
	v_mov_b32_e32 v7, v12
	v_mov_b32_e32 v12, v11
	v_mov_b32_e32 v36, v13
	v_mov_b32_e32 v37, v10
	v_mov_b32_e32 v11, v16
	v_mov_b32_e32 v16, v15
	v_mov_b32_e32 v38, v17
	v_mov_b32_e32 v39, v14
	v_mov_b32_e32 v15, v20
	v_mov_b32_e32 v20, v19
	v_mov_b32_e32 v40, v21
	v_mov_b32_e32 v41, v18
	v_mov_b32_e32 v30, v19
	v_mov_b32_e32 v32, v6
	v_mov_b32_e32 v6, v10
	v_mov_b32_e32 v10, v14
	v_mov_b32_e32 v14, v18
	v_pk_mul_f32 v[8:9], v[22:23], v[8:9] op_sel:[1,0]
	v_pk_mul_f32 v[18:19], v[22:23], v[34:35]
	v_pk_mul_f32 v[12:13], v[22:23], v[12:13] op_sel:[1,0]
	v_pk_mul_f32 v[34:35], v[22:23], v[36:37]
	v_pk_mul_f32 v[16:17], v[22:23], v[16:17] op_sel:[1,0]
	v_pk_mul_f32 v[36:37], v[22:23], v[38:39]
	v_pk_mul_f32 v[20:21], v[22:23], v[20:21] op_sel:[1,0]
	v_pk_mul_f32 v[38:39], v[22:23], v[40:41]
	v_pk_fma_f32 v[8:9], v[22:23], v[32:33], v[8:9] op_sel_hi:[0,1,1] neg_lo:[0,0,1] neg_hi:[0,0,1]
	v_pk_fma_f32 v[18:19], v[22:23], v[24:25], v[18:19] op_sel:[0,0,1] op_sel_hi:[1,1,0]
	v_pk_fma_f32 v[6:7], v[22:23], v[6:7], v[12:13] op_sel_hi:[0,1,1] neg_lo:[0,0,1] neg_hi:[0,0,1]
	v_pk_fma_f32 v[12:13], v[22:23], v[26:27], v[34:35] op_sel:[0,0,1] op_sel_hi:[1,1,0]
	v_pk_fma_f32 v[10:11], v[22:23], v[10:11], v[16:17] op_sel_hi:[0,1,1] neg_lo:[0,0,1] neg_hi:[0,0,1]
	v_pk_fma_f32 v[16:17], v[22:23], v[28:29], v[36:37] op_sel:[0,0,1] op_sel_hi:[1,1,0]
	v_pk_fma_f32 v[14:15], v[22:23], v[14:15], v[20:21] op_sel_hi:[0,1,1] neg_lo:[0,0,1] neg_hi:[0,0,1]
	v_pk_fma_f32 v[20:21], v[22:23], v[30:31], v[38:39] op_sel:[0,0,1] op_sel_hi:[1,1,0]
	v_cndmask_b32_e32 v4, v19, v9, vcc
	v_cndmask_b32_e32 v8, v18, v8, vcc
	v_cndmask_b32_e32 v7, v13, v7, vcc
	v_cndmask_b32_e32 v9, v12, v6, vcc
	v_cndmask_b32_e32 v11, v17, v11, vcc
	v_cndmask_b32_e32 v10, v16, v10, vcc
	v_cndmask_b32_e32 v12, v21, v15, vcc
	v_cndmask_b32_e32 v13, v20, v14, vcc
	v_cvt_pk_bf16_f32 v6, v8, v4
	v_cvt_pk_bf16_f32 v7, v9, v7
	v_cvt_pk_bf16_f32 v8, v10, v11
	v_cvt_pk_bf16_f32 v9, v13, v12
	global_store_dwordx4 v[2:3], v[6:9], off
	v_lshl_add_u64 v[2:3], v[2:3], 0, s[10:11]

; DI unsigned pk2(float lo, float hi) { f32x2_t v = {lo, hi}; bf16x2_t b = __builtin_convertvector(v, bf16x2_t); return __builtin_bit_cast(unsigned, b); }
; DI void s5_tables_late(const Params& p, const int gtid, const int gstr) {
;     ...
;     for (int idx = gtid; idx < 32 * 1024 * 16; idx += gstr) {
;         const int g = idx >> 14, m = (idx >> 4) & 1023, kk0 = (idx & 15) * 8;
;         const int t = m >> 4, c = m & 15, p0 = kk0 & 63;
;         const float4* crp = (const float4*)(cre + (size_t)(g * 16 + c) * 64 + p0);
;         const float4* cip = (const float4*)(cim + (size_t)(g * 16 + c) * 64 + p0);
;         float4 cr0 = crp[0], cr1 = crp[1], ci0 = cip[0], ci1 = cip[1];
;         const float crv[8] = {cr0.x, cr0.y, cr0.z, cr0.w, cr1.x, cr1.y, cr1.z, cr1.w};
;         const float civ[8] = {ci0.x, ci0.y, ci0.z, ci0.w, ci1.x, ci1.y, ci1.z, ci1.w};
;         float o[8];
; #pragma unroll
;         for (int e = 0; e < 8; ++e) {
;             const float2 a = apow[((size_t)g * 65 + t + 1) * 64 + p0 + e];
;             o[e] = (kk0 < 64) ? (crv[e] * a.x - civ[e] * a.y) : -(crv[e] * a.y + civ[e] * a.x);
;         }
;         *(uint4*)(cmat + (size_t)idx * 8) = make_uint4(pk2(o[0], o[1]), pk2(o[2], o[3]), pk2(o[4], o[5]), pk2(o[6], o[7]));
.LBB0_368:
	v_ashrrev_i32_e32 v1, 14, v0
	v_bfe_u32 v4, v0, 4, 4
	v_lshl_or_b32 v8, v1, 4, v4
	v_mul_i32_i24_e32 v10, 0x41, v1
	v_bfe_u32 v6, v0, 8, 6
	v_mov_b32_e32 v7, v5
	v_ashrrev_i32_e32 v9, 31, v8
	v_ashrrev_i32_e32 v11, 31, v10
	v_and_b32_e32 v12, 56, v22
	v_lshlrev_b64 v[8:9], 8, v[8:9]
	v_lshl_add_u64 v[6:7], v[10:11], 0, v[6:7]
	v_lshlrev_b32_e32 v4, 2, v12
	v_lshl_add_u64 v[10:11], s[38:39], 0, v[8:9]
	v_lshl_add_u64 v[8:9], s[40:41], 0, v[8:9]
	v_lshlrev_b64 v[6:7], 9, v[6:7]
	v_lshl_add_u64 v[36:37], v[10:11], 0, v[4:5]
	v_lshl_add_u64 v[14:15], v[8:9], 0, v[4:5]
	v_lshl_add_u64 v[6:7], s[4:5], 0, v[6:7]
	v_lshlrev_b32_e32 v4, 3, v12
	v_lshl_add_u64 v[32:33], v[6:7], 0, v[4:5]
	global_load_dwordx4 v[128:131], v[36:37], off
	global_load_dwordx4 v[132:135], v[14:15], off offset:16
	s_nop 0
	global_load_dwordx4 v[136:139], v[14:15], off
	s_nop 0
	global_load_dwordx4 v[140:143], v[32:33], off offset:512
	global_load_dwordx4 v[144:147], v[32:33], off offset:528
	global_load_dwordx4 v[148:151], v[32:33], off offset:544
	s_nop 0
	global_load_dwordx4 v[152:155], v[32:33], off offset:560
	s_nop 0
	global_load_dwordx4 v[156:159], v[36:37], off offset:16
	v_and_b32_e32 v230, 8, v0
	v_add_u32_e32 v0, s0, v0
	v_add_u32_e32 v22, s1, v22
	v_ashrrev_i32_e32 v1, 14, v0
	v_bfe_u32 v4, v0, 4, 4
	v_lshl_or_b32 v8, v1, 4, v4
	v_mul_i32_i24_e32 v10, 0x41, v1
	v_bfe_u32 v6, v0, 8, 6
	v_mov_b32_e32 v7, v5
	v_ashrrev_i32_e32 v9, 31, v8
	v_ashrrev_i32_e32 v11, 31, v10
	v_and_b32_e32 v12, 56, v22
	v_lshlrev_b64 v[8:9], 8, v[8:9]
	v_lshl_add_u64 v[6:7], v[10:11], 0, v[6:7]
	v_lshlrev_b32_e32 v4, 2, v12
	v_lshl_add_u64 v[10:11], s[38:39], 0, v[8:9]
	v_lshl_add_u64 v[8:9], s[40:41], 0, v[8:9]
	v_lshlrev_b64 v[6:7], 9, v[6:7]
	v_lshl_add_u64 v[36:37], v[10:11], 0, v[4:5]
	v_lshl_add_u64 v[14:15], v[8:9], 0, v[4:5]
	v_lshl_add_u64 v[6:7], s[4:5], 0, v[6:7]
	v_lshlrev_b32_e32 v4, 3, v12
	v_lshl_add_u64 v[32:33], v[6:7], 0, v[4:5]
	global_load_dwordx4 v[164:167], v[36:37], off
	global_load_dwordx4 v[168:171], v[14:15], off offset:16
	s_nop 0
	global_load_dwordx4 v[172:175], v[14:15], off
	s_nop 0
	global_load_dwordx4 v[176:179], v[32:33], off offset:512
	global_load_dwordx4 v[180:183], v[32:33], off offset:528
	global_load_dwordx4 v[184:187], v[32:33], off offset:544
	s_nop 0
	global_load_dwordx4 v[188:191], v[32:33], off offset:560
	s_nop 0
	global_load_dwordx4 v[192:195], v[36:37], off offset:16
	v_and_b32_e32 v231, 8, v0
	v_add_u32_e32 v0, s0, v0
	v_add_u32_e32 v22, s1, v22
	v_ashrrev_i32_e32 v1, 14, v0
	v_bfe_u32 v4, v0, 4, 4
	v_lshl_or_b32 v8, v1, 4, v4
	v_mul_i32_i24_e32 v10, 0x41, v1
	v_bfe_u32 v6, v0, 8, 6
	v_mov_b32_e32 v7, v5
	v_ashrrev_i32_e32 v9, 31, v8
	v_ashrrev_i32_e32 v11, 31, v10
	v_and_b32_e32 v12, 56, v22
	v_lshlrev_b64 v[8:9], 8, v[8:9]
	v_lshl_add_u64 v[6:7], v[10:11], 0, v[6:7]
	v_lshlrev_b32_e32 v4, 2, v12
	v_lshl_add_u64 v[10:11], s[38:39], 0, v[8:9]
	v_lshl_add_u64 v[8:9], s[40:41], 0, v[8:9]
	v_lshlrev_b64 v[6:7], 9, v[6:7]
	v_lshl_add_u64 v[36:37], v[10:11], 0, v[4:5]
	v_lshl_add_u64 v[14:15], v[8:9], 0, v[4:5]
	v_lshl_add_u64 v[6:7], s[4:5], 0, v[6:7]
	v_lshlrev_b32_e32 v4, 3, v12
	v_lshl_add_u64 v[32:33], v[6:7], 0, v[4:5]
	global_load_dwordx4 v[196:199], v[36:37], off
	global_load_dwordx4 v[200:203], v[14:15], off offset:16
	s_nop 0
	global_load_dwordx4 v[204:207], v[14:15], off
	s_nop 0
	global_load_dwordx4 v[208:211], v[32:33], off offset:512
	global_load_dwordx4 v[212:215], v[32:33], off offset:528
	global_load_dwordx4 v[216:219], v[32:33], off offset:544
	s_nop 0
	global_load_dwordx4 v[220:223], v[32:33], off offset:560
	s_nop 0
	global_load_dwordx4 v[224:227], v[36:37], off offset:16
	v_and_b32_e32 v232, 8, v0
	v_add_u32_e32 v0, s0, v0
	v_add_u32_e32 v22, s1, v22
	s_waitcnt vmcnt(16)
	v_mov_b64_e32 v[6:7], v[128:129]
	v_mov_b64_e32 v[8:9], v[130:131]
	v_mov_b64_e32 v[10:11], v[132:133]
	v_mov_b64_e32 v[12:13], v[134:135]
	v_mov_b64_e32 v[14:15], v[136:137]
	v_mov_b64_e32 v[16:17], v[138:139]
	v_mov_b64_e32 v[18:19], v[140:141]
	v_mov_b64_e32 v[20:21], v[142:143]
	v_mov_b64_e32 v[24:25], v[144:145]
	v_mov_b64_e32 v[26:27], v[146:147]
	v_mov_b64_e32 v[28:29], v[148:149]
	v_mov_b64_e32 v[30:31], v[150:151]
	v_mov_b64_e32 v[32:33], v[152:153]
	v_mov_b64_e32 v[34:35], v[154:155]
	v_mov_b64_e32 v[36:37], v[156:157]
	v_mov_b64_e32 v[38:39], v[158:159]
	v_cmp_eq_u32_e32 vcc, 0, v230
	s_nop 1
	v_mov_b32_e32 v41, v20
	v_mov_b32_e32 v20, v19
	v_mov_b32_e32 v19, v26
	v_mov_b32_e32 v26, v25
	v_mov_b32_e32 v25, v30
	v_mov_b32_e32 v30, v29
	v_mov_b32_e32 v29, v34
	v_mov_b32_e32 v34, v33
	v_mov_b32_e32 v40, v18
	v_mov_b32_e32 v18, v24
	v_mov_b32_e32 v24, v28
	v_mov_b32_e32 v28, v32
	v_pk_mul_f32 v[32:33], v[14:15], v[20:21]
	v_pk_mul_f32 v[20:21], v[6:7], v[20:21]
	v_pk_mul_f32 v[42:43], v[16:17], v[26:27]
	v_pk_mul_f32 v[26:27], v[8:9], v[26:27]
	v_pk_mul_f32 v[46:47], v[10:11], v[30:31]
	v_pk_mul_f32 v[30:31], v[36:37], v[30:31]
	v_pk_mul_f32 v[48:49], v[12:13], v[34:35]
	v_pk_mul_f32 v[34:35], v[38:39], v[34:35]
	v_pk_fma_f32 v[6:7], v[6:7], v[40:41], v[32:33] neg_lo:[0,0,1] neg_hi:[0,0,1]
	v_pk_fma_f32 v[14:15], v[14:15], v[40:41], v[20:21]
	v_pk_fma_f32 v[8:9], v[8:9], v[18:19], v[42:43] neg_lo:[0,0,1] neg_hi:[0,0,1]
	v_pk_fma_f32 v[16:17], v[16:17], v[18:19], v[26:27]
	v_pk_fma_f32 v[18:19], v[36:37], v[24:25], v[46:47] neg_lo:[0,0,1] neg_hi:[0,0,1]
	v_pk_fma_f32 v[10:11], v[10:11], v[24:25], v[30:31]
	v_pk_fma_f32 v[20:21], v[38:39], v[28:29], v[48:49] neg_lo:[0,0,1] neg_hi:[0,0,1]
	v_pk_fma_f32 v[12:13], v[12:13], v[28:29], v[34:35]
	v_cndmask_b32_e64 v1, -v15, v7, vcc
	v_cndmask_b32_e64 v4, -v14, v6, vcc
	v_cndmask_b32_e64 v7, -v17, v9, vcc
; DI unsigned pk2(float lo, float hi) { f32x2_t v = {lo, hi}; bf16x2_t b = __builtin_convertvector(v, bf16x2_t); return __builtin_bit_cast(unsigned, b); }
; DI void s5_tables_late(const Params& p, const int gtid, const int gstr) {
;     ...
;     for (int idx = gtid; idx < 32 * 1024 * 16; idx += gstr) {
;         const int g = idx >> 14, m = (idx >> 4) & 1023, kk0 = (idx & 15) * 8;
;         const int t = m >> 4, c = m & 15, p0 = kk0 & 63;
;         const float4* crp = (const float4*)(cre + (size_t)(g * 16 + c) * 64 + p0);
;         const float4* cip = (const float4*)(cim + (size_t)(g * 16 + c) * 64 + p0);
;         float4 cr0 = crp[0], cr1 = crp[1], ci0 = cip[0], ci1 = cip[1];
;         const float crv[8] = {cr0.x, cr0.y, cr0.z, cr0.w, cr1.x, cr1.y, cr1.z, cr1.w};
;         const float civ[8] = {ci0.x, ci0.y, ci0.z, ci0.w, ci1.x, ci1.y, ci1.z, ci1.w};
;         float o[8];
; #pragma unroll
;         for (int e = 0; e < 8; ++e) {
;             const float2 a = apow[((size_t)g * 65 + t + 1) * 64 + p0 + e];
;             o[e] = (kk0 < 64) ? (crv[e] * a.x - civ[e] * a.y) : -(crv[e] * a.y + civ[e] * a.x);
;         }
;         *(uint4*)(cmat + (size_t)idx * 8) = make_uint4(pk2(o[0], o[1]), pk2(o[2], o[3]), pk2(o[4], o[5]), pk2(o[6], o[7]));
	v_cndmask_b32_e64 v8, -v16, v8, vcc
	v_cndmask_b32_e64 v9, -v11, v19, vcc
	v_cndmask_b32_e64 v10, -v10, v18, vcc
	v_cndmask_b32_e64 v11, -v13, v21, vcc
	v_cndmask_b32_e64 v12, -v12, v20, vcc
	v_cvt_pk_bf16_f32 v6, v4, v1
	v_cvt_pk_bf16_f32 v7, v8, v7
	v_cvt_pk_bf16_f32 v8, v10, v9
	v_cvt_pk_bf16_f32 v9, v12, v11
	global_store_dwordx4 v[2:3], v[6:9], off
	v_lshl_add_u64 v[2:3], v[2:3], 0, s[8:9]
	v_ashrrev_i32_e32 v1, 14, v0
	v_bfe_u32 v4, v0, 4, 4
	v_lshl_or_b32 v8, v1, 4, v4
	v_mul_i32_i24_e32 v10, 0x41, v1
	v_bfe_u32 v6, v0, 8, 6
	v_mov_b32_e32 v7, v5
	v_ashrrev_i32_e32 v9, 31, v8
	v_ashrrev_i32_e32 v11, 31, v10
	v_and_b32_e32 v12, 56, v22
	v_lshlrev_b64 v[8:9], 8, v[8:9]
	v_lshl_add_u64 v[6:7], v[10:11], 0, v[6:7]
	v_lshlrev_b32_e32 v4, 2, v12
	v_lshl_add_u64 v[10:11], s[38:39], 0, v[8:9]
	v_lshl_add_u64 v[8:9], s[40:41], 0, v[8:9]
	v_lshlrev_b64 v[6:7], 9, v[6:7]
	v_lshl_add_u64 v[36:37], v[10:11], 0, v[4:5]
	v_lshl_add_u64 v[14:15], v[8:9], 0, v[4:5]
	v_lshl_add_u64 v[6:7], s[4:5], 0, v[6:7]
	v_lshlrev_b32_e32 v4, 3, v12
	v_lshl_add_u64 v[32:33], v[6:7], 0, v[4:5]
	global_load_dwordx4 v[128:131], v[36:37], off
	global_load_dwordx4 v[132:135], v[14:15], off offset:16
	s_nop 0
	global_load_dwordx4 v[136:139], v[14:15], off
	s_nop 0
	global_load_dwordx4 v[140:143], v[32:33], off offset:512
	global_load_dwordx4 v[144:147], v[32:33], off offset:528
	global_load_dwordx4 v[148:151], v[32:33], off offset:544
	s_nop 0
	global_load_dwordx4 v[152:155], v[32:33], off offset:560
	s_nop 0
	global_load_dwordx4 v[156:159], v[36:37], off offset:16
	v_and_b32_e32 v233, 8, v0
	v_add_u32_e32 v0, s0, v0
	v_add_u32_e32 v22, s1, v22
	s_waitcnt vmcnt(17)
	v_mov_b64_e32 v[6:7], v[164:165]
	v_mov_b64_e32 v[8:9], v[166:167]
	v_mov_b64_e32 v[10:11], v[168:169]
	v_mov_b64_e32 v[12:13], v[170:171]
	v_mov_b64_e32 v[14:15], v[172:173]
	v_mov_b64_e32 v[16:17], v[174:175]
	v_mov_b64_e32 v[18:19], v[176:177]
	v_mov_b64_e32 v[20:21], v[178:179]
	v_mov_b64_e32 v[24:25], v[180:181]
	v_mov_b64_e32 v[26:27], v[182:183]
	v_mov_b64_e32 v[28:29], v[184:185]
	v_mov_b64_e32 v[30:31], v[186:187]
	v_mov_b64_e32 v[32:33], v[188:189]
	v_mov_b64_e32 v[34:35], v[190:191]
	v_mov_b64_e32 v[36:37], v[192:193]
	v_mov_b64_e32 v[38:39], v[194:195]
	v_cmp_eq_u32_e32 vcc, 0, v231
	s_nop 1
	v_mov_b32_e32 v41, v20
	v_mov_b32_e32 v20, v19
	v_mov_b32_e32 v19, v26
	v_mov_b32_e32 v26, v25
	v_mov_b32_e32 v25, v30
	v_mov_b32_e32 v30, v29
	v_mov_b32_e32 v29, v34
	v_mov_b32_e32 v34, v33
	v_mov_b32_e32 v40, v18
	v_mov_b32_e32 v18, v24
	v_mov_b32_e32 v24, v28
	v_mov_b32_e32 v28, v32
	v_pk_mul_f32 v[32:33], v[14:15], v[20:21]
	v_pk_mul_f32 v[20:21], v[6:7], v[20:21]
	v_pk_mul_f32 v[42:43], v[16:17], v[26:27]
	v_pk_mul_f32 v[26:27], v[8:9], v[26:27]
	v_pk_mul_f32 v[46:47], v[10:11], v[30:31]
	v_pk_mul_f32 v[30:31], v[36:37], v[30:31]
	v_pk_mul_f32 v[48:49], v[12:13], v[34:35]
	v_pk_mul_f32 v[34:35], v[38:39], v[34:35]
	v_pk_fma_f32 v[6:7], v[6:7], v[40:41], v[32:33] neg_lo:[0,0,1] neg_hi:[0,0,1]
	v_pk_fma_f32 v[14:15], v[14:15], v[40:41], v[20:21]
	v_pk_fma_f32 v[8:9], v[8:9], v[18:19], v[42:43] neg_lo:[0,0,1] neg_hi:[0,0,1]
	v_pk_fma_f32 v[16:17], v[16:17], v[18:19], v[26:27]
	v_pk_fma_f32 v[18:19], v[36:37], v[24:25], v[46:47] neg_lo:[0,0,1] neg_hi:[0,0,1]
	v_pk_fma_f32 v[10:11], v[10:11], v[24:25], v[30:31]
	v_pk_fma_f32 v[20:21], v[38:39], v[28:29], v[48:49] neg_lo:[0,0,1] neg_hi:[0,0,1]
	v_pk_fma_f32 v[12:13], v[12:13], v[28:29], v[34:35]
	v_cndmask_b32_e64 v1, -v15, v7, vcc
	v_cndmask_b32_e64 v4, -v14, v6, vcc
	v_cndmask_b32_e64 v7, -v17, v9, vcc
	v_cndmask_b32_e64 v8, -v16, v8, vcc
	v_cndmask_b32_e64 v9, -v11, v19, vcc
	v_cndmask_b32_e64 v10, -v10, v18, vcc
	v_cndmask_b32_e64 v11, -v13, v21, vcc
	v_cndmask_b32_e64 v12, -v12, v20, vcc
	v_cvt_pk_bf16_f32 v6, v4, v1
	v_cvt_pk_bf16_f32 v7, v8, v7
	v_cvt_pk_bf16_f32 v8, v10, v9
	v_cvt_pk_bf16_f32 v9, v12, v11
	global_store_dwordx4 v[2:3], v[6:9], off
	v_lshl_add_u64 v[2:3], v[2:3], 0, s[8:9]
	v_ashrrev_i32_e32 v1, 14, v0
	v_bfe_u32 v4, v0, 4, 4
	v_lshl_or_b32 v8, v1, 4, v4
	v_mul_i32_i24_e32 v10, 0x41, v1
	v_bfe_u32 v6, v0, 8, 6
	v_mov_b32_e32 v7, v5
	v_ashrrev_i32_e32 v9, 31, v8
	v_ashrrev_i32_e32 v11, 31, v10
	v_and_b32_e32 v12, 56, v22
	v_lshlrev_b64 v[8:9], 8, v[8:9]
	v_lshl_add_u64 v[6:7], v[10:11], 0, v[6:7]
	v_lshlrev_b32_e32 v4, 2, v12
	v_lshl_add_u64 v[10:11], s[38:39], 0, v[8:9]
	v_lshl_add_u64 v[8:9], s[40:41], 0, v[8:9]
	v_lshlrev_b64 v[6:7], 9, v[6:7]
	v_lshl_add_u64 v[36:37], v[10:11], 0, v[4:5]
	v_lshl_add_u64 v[14:15], v[8:9], 0, v[4:5]
	v_lshl_add_u64 v[6:7], s[4:5], 0, v[6:7]
	v_lshlrev_b32_e32 v4, 3, v12
	v_lshl_add_u64 v[32:33], v[6:7], 0, v[4:5]
	global_load_dwordx4 v[164:167], v[36:37], off
	global_load_dwordx4 v[168:171], v[14:15], off offset:16
	s_nop 0
	global_load_dwordx4 v[172:175], v[14:15], off
	s_nop 0
	global_load_dwordx4 v[176:179], v[32:33], off offset:512
	global_load_dwordx4 v[180:183], v[32:33], off offset:528
	global_load_dwordx4 v[184:187], v[32:33], off offset:544
	s_nop 0
	global_load_dwordx4 v[188:191], v[32:33], off offset:560
	s_nop 0
	global_load_dwordx4 v[192:195], v[36:37], off offset:16
	v_and_b32_e32 v234, 8, v0
	v_add_u32_e32 v0, s0, v0
	v_add_u32_e32 v22, s1, v22
	s_waitcnt vmcnt(18)
; DI unsigned pk2(float lo, float hi) { f32x2_t v = {lo, hi}; bf16x2_t b = __builtin_convertvector(v, bf16x2_t); return __builtin_bit_cast(unsigned, b); }
; DI void s5_tables_late(const Params& p, const int gtid, const int gstr) {
;     ...
;     for (int idx = gtid; idx < 32 * 1024 * 16; idx += gstr) {
;         const int g = idx >> 14, m = (idx >> 4) & 1023, kk0 = (idx & 15) * 8;
;         const int t = m >> 4, c = m & 15, p0 = kk0 & 63;
;         const float4* crp = (const float4*)(cre + (size_t)(g * 16 + c) * 64 + p0);
;         const float4* cip = (const float4*)(cim + (size_t)(g * 16 + c) * 64 + p0);
;         float4 cr0 = crp[0], cr1 = crp[1], ci0 = cip[0], ci1 = cip[1];
;         const float crv[8] = {cr0.x, cr0.y, cr0.z, cr0.w, cr1.x, cr1.y, cr1.z, cr1.w};
;         const float civ[8] = {ci0.x, ci0.y, ci0.z, ci0.w, ci1.x, ci1.y, ci1.z, ci1.w};
;         float o[8];
; #pragma unroll
;         for (int e = 0; e < 8; ++e) {
;             const float2 a = apow[((size_t)g * 65 + t + 1) * 64 + p0 + e];
;             o[e] = (kk0 < 64) ? (crv[e] * a.x - civ[e] * a.y) : -(crv[e] * a.y + civ[e] * a.x);
;         }
;         *(uint4*)(cmat + (size_t)idx * 8) = make_uint4(pk2(o[0], o[1]), pk2(o[2], o[3]), pk2(o[4], o[5]), pk2(o[6], o[7]));
	v_mov_b64_e32 v[6:7], v[196:197]
	v_mov_b64_e32 v[8:9], v[198:199]
	v_mov_b64_e32 v[10:11], v[200:201]
	v_mov_b64_e32 v[12:13], v[202:203]
	v_mov_b64_e32 v[14:15], v[204:205]
	v_mov_b64_e32 v[16:17], v[206:207]
	v_mov_b64_e32 v[18:19], v[208:209]
	v_mov_b64_e32 v[20:21], v[210:211]
	v_mov_b64_e32 v[24:25], v[212:213]
	v_mov_b64_e32 v[26:27], v[214:215]
	v_mov_b64_e32 v[28:29], v[216:217]
	v_mov_b64_e32 v[30:31], v[218:219]
	v_mov_b64_e32 v[32:33], v[220:221]
	v_mov_b64_e32 v[34:35], v[222:223]
	v_mov_b64_e32 v[36:37], v[224:225]
	v_mov_b64_e32 v[38:39], v[226:227]
	v_cmp_eq_u32_e32 vcc, 0, v232
	s_nop 1
	v_mov_b32_e32 v41, v20
	v_mov_b32_e32 v20, v19
	v_mov_b32_e32 v19, v26
	v_mov_b32_e32 v26, v25
	v_mov_b32_e32 v25, v30
	v_mov_b32_e32 v30, v29
	v_mov_b32_e32 v29, v34
	v_mov_b32_e32 v34, v33
	v_mov_b32_e32 v40, v18
	v_mov_b32_e32 v18, v24
	v_mov_b32_e32 v24, v28
	v_mov_b32_e32 v28, v32
	v_pk_mul_f32 v[32:33], v[14:15], v[20:21]
	v_pk_mul_f32 v[20:21], v[6:7], v[20:21]
	v_pk_mul_f32 v[42:43], v[16:17], v[26:27]
	v_pk_mul_f32 v[26:27], v[8:9], v[26:27]
	v_pk_mul_f32 v[46:47], v[10:11], v[30:31]
	v_pk_mul_f32 v[30:31], v[36:37], v[30:31]
	v_pk_mul_f32 v[48:49], v[12:13], v[34:35]
	v_pk_mul_f32 v[34:35], v[38:39], v[34:35]
	v_pk_fma_f32 v[6:7], v[6:7], v[40:41], v[32:33] neg_lo:[0,0,1] neg_hi:[0,0,1]
	v_pk_fma_f32 v[14:15], v[14:15], v[40:41], v[20:21]
	v_pk_fma_f32 v[8:9], v[8:9], v[18:19], v[42:43] neg_lo:[0,0,1] neg_hi:[0,0,1]
	v_pk_fma_f32 v[16:17], v[16:17], v[18:19], v[26:27]
	v_pk_fma_f32 v[18:19], v[36:37], v[24:25], v[46:47] neg_lo:[0,0,1] neg_hi:[0,0,1]
	v_pk_fma_f32 v[10:11], v[10:11], v[24:25], v[30:31]
	v_pk_fma_f32 v[20:21], v[38:39], v[28:29], v[48:49] neg_lo:[0,0,1] neg_hi:[0,0,1]
	v_pk_fma_f32 v[12:13], v[12:13], v[28:29], v[34:35]
	v_cndmask_b32_e64 v1, -v15, v7, vcc
	v_cndmask_b32_e64 v4, -v14, v6, vcc
	v_cndmask_b32_e64 v7, -v17, v9, vcc
	v_cndmask_b32_e64 v8, -v16, v8, vcc
	v_cndmask_b32_e64 v9, -v11, v19, vcc
	v_cndmask_b32_e64 v10, -v10, v18, vcc
	v_cndmask_b32_e64 v11, -v13, v21, vcc
	v_cndmask_b32_e64 v12, -v12, v20, vcc
	v_cvt_pk_bf16_f32 v6, v4, v1
	v_cvt_pk_bf16_f32 v7, v8, v7
	v_cvt_pk_bf16_f32 v8, v10, v9
	v_cvt_pk_bf16_f32 v9, v12, v11
	global_store_dwordx4 v[2:3], v[6:9], off
	v_lshl_add_u64 v[2:3], v[2:3], 0, s[8:9]
	v_ashrrev_i32_e32 v1, 14, v0
	v_bfe_u32 v4, v0, 4, 4
	v_lshl_or_b32 v8, v1, 4, v4
	v_mul_i32_i24_e32 v10, 0x41, v1
	v_bfe_u32 v6, v0, 8, 6
	v_mov_b32_e32 v7, v5
	v_ashrrev_i32_e32 v9, 31, v8
	v_ashrrev_i32_e32 v11, 31, v10
	v_and_b32_e32 v12, 56, v22
	v_lshlrev_b64 v[8:9], 8, v[8:9]
	v_lshl_add_u64 v[6:7], v[10:11], 0, v[6:7]
	v_lshlrev_b32_e32 v4, 2, v12
	v_lshl_add_u64 v[10:11], s[38:39], 0, v[8:9]
	v_lshl_add_u64 v[8:9], s[40:41], 0, v[8:9]
	v_lshlrev_b64 v[6:7], 9, v[6:7]
	v_lshl_add_u64 v[36:37], v[10:11], 0, v[4:5]
	v_lshl_add_u64 v[14:15], v[8:9], 0, v[4:5]
	v_lshl_add_u64 v[6:7], s[4:5], 0, v[6:7]
	v_lshlrev_b32_e32 v4, 3, v12
	v_lshl_add_u64 v[32:33], v[6:7], 0, v[4:5]
	global_load_dwordx4 v[196:199], v[36:37], off
	global_load_dwordx4 v[200:203], v[14:15], off offset:16
	s_nop 0
	global_load_dwordx4 v[204:207], v[14:15], off
	s_nop 0
	global_load_dwordx4 v[208:211], v[32:33], off offset:512
	global_load_dwordx4 v[212:215], v[32:33], off offset:528
	global_load_dwordx4 v[216:219], v[32:33], off offset:544
	s_nop 0
	global_load_dwordx4 v[220:223], v[32:33], off offset:560
	s_nop 0
	global_load_dwordx4 v[224:227], v[36:37], off offset:16
	v_and_b32_e32 v235, 8, v0
	v_add_u32_e32 v0, s0, v0
	v_add_u32_e32 v22, s1, v22
	s_waitcnt vmcnt(18)
	v_mov_b64_e32 v[6:7], v[128:129]
	v_mov_b64_e32 v[8:9], v[130:131]
	v_mov_b64_e32 v[10:11], v[132:133]
	v_mov_b64_e32 v[12:13], v[134:135]
	v_mov_b64_e32 v[14:15], v[136:137]
	v_mov_b64_e32 v[16:17], v[138:139]
	v_mov_b64_e32 v[18:19], v[140:141]
	v_mov_b64_e32 v[20:21], v[142:143]
	v_mov_b64_e32 v[24:25], v[144:145]
	v_mov_b64_e32 v[26:27], v[146:147]
	v_mov_b64_e32 v[28:29], v[148:149]
	v_mov_b64_e32 v[30:31], v[150:151]
	v_mov_b64_e32 v[32:33], v[152:153]
	v_mov_b64_e32 v[34:35], v[154:155]
	v_mov_b64_e32 v[36:37], v[156:157]
	v_mov_b64_e32 v[38:39], v[158:159]
	v_cmp_eq_u32_e32 vcc, 0, v233
	s_nop 1
	v_mov_b32_e32 v41, v20
	v_mov_b32_e32 v20, v19
	v_mov_b32_e32 v19, v26
	v_mov_b32_e32 v26, v25
	v_mov_b32_e32 v25, v30
	v_mov_b32_e32 v30, v29
	v_mov_b32_e32 v29, v34
	v_mov_b32_e32 v34, v33
	v_mov_b32_e32 v40, v18
	v_mov_b32_e32 v18, v24
	v_mov_b32_e32 v24, v28
	v_mov_b32_e32 v28, v32
	v_pk_mul_f32 v[32:33], v[14:15], v[20:21]
	v_pk_mul_f32 v[20:21], v[6:7], v[20:21]
	v_pk_mul_f32 v[42:43], v[16:17], v[26:27]
	v_pk_mul_f32 v[26:27], v[8:9], v[26:27]
	v_pk_mul_f32 v[46:47], v[10:11], v[30:31]
	v_pk_mul_f32 v[30:31], v[36:37], v[30:31]
	v_pk_mul_f32 v[48:49], v[12:13], v[34:35]
	v_pk_mul_f32 v[34:35], v[38:39], v[34:35]
	v_pk_fma_f32 v[6:7], v[6:7], v[40:41], v[32:33] neg_lo:[0,0,1] neg_hi:[0,0,1]
	v_pk_fma_f32 v[14:15], v[14:15], v[40:41], v[20:21]
	v_pk_fma_f32 v[8:9], v[8:9], v[18:19], v[42:43] neg_lo:[0,0,1] neg_hi:[0,0,1]
	v_pk_fma_f32 v[16:17], v[16:17], v[18:19], v[26:27]
	v_pk_fma_f32 v[18:19], v[36:37], v[24:25], v[46:47] neg_lo:[0,0,1] neg_hi:[0,0,1]
	v_pk_fma_f32 v[10:11], v[10:11], v[24:25], v[30:31]
	v_pk_fma_f32 v[20:21], v[38:39], v[28:29], v[48:49] neg_lo:[0,0,1] neg_hi:[0,0,1]
	v_pk_fma_f32 v[12:13], v[12:13], v[28:29], v[34:35]
	v_cndmask_b32_e64 v1, -v15, v7, vcc
	v_cndmask_b32_e64 v4, -v14, v6, vcc
	v_cndmask_b32_e64 v7, -v17, v9, vcc
	v_cndmask_b32_e64 v8, -v16, v8, vcc
	v_cndmask_b32_e64 v9, -v11, v19, vcc
	v_cndmask_b32_e64 v10, -v10, v18, vcc
	v_cndmask_b32_e64 v11, -v13, v21, vcc
	v_cndmask_b32_e64 v12, -v12, v20, vcc
; DI unsigned pk2(float lo, float hi) { f32x2_t v = {lo, hi}; bf16x2_t b = __builtin_convertvector(v, bf16x2_t); return __builtin_bit_cast(unsigned, b); }
; DI void s5_tables_late(const Params& p, const int gtid, const int gstr) {
;     ...
;     for (int idx = gtid; idx < 32 * 1024 * 16; idx += gstr) {
;         const int g = idx >> 14, m = (idx >> 4) & 1023, kk0 = (idx & 15) * 8;
;         const int t = m >> 4, c = m & 15, p0 = kk0 & 63;
;         const float4* crp = (const float4*)(cre + (size_t)(g * 16 + c) * 64 + p0);
;         const float4* cip = (const float4*)(cim + (size_t)(g * 16 + c) * 64 + p0);
;         float4 cr0 = crp[0], cr1 = crp[1], ci0 = cip[0], ci1 = cip[1];
;         const float crv[8] = {cr0.x, cr0.y, cr0.z, cr0.w, cr1.x, cr1.y, cr1.z, cr1.w};
;         const float civ[8] = {ci0.x, ci0.y, ci0.z, ci0.w, ci1.x, ci1.y, ci1.z, ci1.w};
;         float o[8];
; #pragma unroll
;         for (int e = 0; e < 8; ++e) {
;             const float2 a = apow[((size_t)g * 65 + t + 1) * 64 + p0 + e];
;             o[e] = (kk0 < 64) ? (crv[e] * a.x - civ[e] * a.y) : -(crv[e] * a.y + civ[e] * a.x);
;         }
;         *(uint4*)(cmat + (size_t)idx * 8) = make_uint4(pk2(o[0], o[1]), pk2(o[2], o[3]), pk2(o[4], o[5]), pk2(o[6], o[7]));
	v_cvt_pk_bf16_f32 v6, v4, v1
	v_cvt_pk_bf16_f32 v7, v8, v7
	v_cvt_pk_bf16_f32 v8, v10, v9
	v_cvt_pk_bf16_f32 v9, v12, v11
	global_store_dwordx4 v[2:3], v[6:9], off
	v_lshl_add_u64 v[2:3], v[2:3], 0, s[8:9]
	v_ashrrev_i32_e32 v1, 14, v0
	v_bfe_u32 v4, v0, 4, 4
	v_lshl_or_b32 v8, v1, 4, v4
	v_mul_i32_i24_e32 v10, 0x41, v1
	v_bfe_u32 v6, v0, 8, 6
	v_mov_b32_e32 v7, v5
	v_ashrrev_i32_e32 v9, 31, v8
	v_ashrrev_i32_e32 v11, 31, v10
	v_and_b32_e32 v12, 56, v22
	v_lshlrev_b64 v[8:9], 8, v[8:9]
	v_lshl_add_u64 v[6:7], v[10:11], 0, v[6:7]
	v_lshlrev_b32_e32 v4, 2, v12
	v_lshl_add_u64 v[10:11], s[38:39], 0, v[8:9]
	v_lshl_add_u64 v[8:9], s[40:41], 0, v[8:9]
	v_lshlrev_b64 v[6:7], 9, v[6:7]
	v_lshl_add_u64 v[36:37], v[10:11], 0, v[4:5]
	v_lshl_add_u64 v[14:15], v[8:9], 0, v[4:5]
	v_lshl_add_u64 v[6:7], s[4:5], 0, v[6:7]
	v_lshlrev_b32_e32 v4, 3, v12
	v_lshl_add_u64 v[32:33], v[6:7], 0, v[4:5]
	global_load_dwordx4 v[128:131], v[36:37], off
	global_load_dwordx4 v[132:135], v[14:15], off offset:16
	s_nop 0
	global_load_dwordx4 v[136:139], v[14:15], off
	s_nop 0
	global_load_dwordx4 v[140:143], v[32:33], off offset:512
	global_load_dwordx4 v[144:147], v[32:33], off offset:528
	global_load_dwordx4 v[148:151], v[32:33], off offset:544
	s_nop 0
	global_load_dwordx4 v[152:155], v[32:33], off offset:560
	s_nop 0
	global_load_dwordx4 v[156:159], v[36:37], off offset:16
	v_and_b32_e32 v236, 8, v0
	v_add_u32_e32 v0, s0, v0
	v_add_u32_e32 v22, s1, v22
	s_waitcnt vmcnt(18)
	v_mov_b64_e32 v[6:7], v[164:165]
	v_mov_b64_e32 v[8:9], v[166:167]
	v_mov_b64_e32 v[10:11], v[168:169]
	v_mov_b64_e32 v[12:13], v[170:171]
	v_mov_b64_e32 v[14:15], v[172:173]
	v_mov_b64_e32 v[16:17], v[174:175]
	v_mov_b64_e32 v[18:19], v[176:177]
	v_mov_b64_e32 v[20:21], v[178:179]
	v_mov_b64_e32 v[24:25], v[180:181]
	v_mov_b64_e32 v[26:27], v[182:183]
	v_mov_b64_e32 v[28:29], v[184:185]
	v_mov_b64_e32 v[30:31], v[186:187]
	v_mov_b64_e32 v[32:33], v[188:189]
	v_mov_b64_e32 v[34:35], v[190:191]
	v_mov_b64_e32 v[36:37], v[192:193]
	v_mov_b64_e32 v[38:39], v[194:195]
	v_cmp_eq_u32_e32 vcc, 0, v234
	s_nop 1
	v_mov_b32_e32 v41, v20
	v_mov_b32_e32 v20, v19
	v_mov_b32_e32 v19, v26
	v_mov_b32_e32 v26, v25
	v_mov_b32_e32 v25, v30
	v_mov_b32_e32 v30, v29
	v_mov_b32_e32 v29, v34
	v_mov_b32_e32 v34, v33
	v_mov_b32_e32 v40, v18
	v_mov_b32_e32 v18, v24
	v_mov_b32_e32 v24, v28
	v_mov_b32_e32 v28, v32
	v_pk_mul_f32 v[32:33], v[14:15], v[20:21]
	v_pk_mul_f32 v[20:21], v[6:7], v[20:21]
	v_pk_mul_f32 v[42:43], v[16:17], v[26:27]
	v_pk_mul_f32 v[26:27], v[8:9], v[26:27]
	v_pk_mul_f32 v[46:47], v[10:11], v[30:31]
	v_pk_mul_f32 v[30:31], v[36:37], v[30:31]
	v_pk_mul_f32 v[48:49], v[12:13], v[34:35]
	v_pk_mul_f32 v[34:35], v[38:39], v[34:35]
	v_pk_fma_f32 v[6:7], v[6:7], v[40:41], v[32:33] neg_lo:[0,0,1] neg_hi:[0,0,1]
	v_pk_fma_f32 v[14:15], v[14:15], v[40:41], v[20:21]
	v_pk_fma_f32 v[8:9], v[8:9], v[18:19], v[42:43] neg_lo:[0,0,1] neg_hi:[0,0,1]
	v_pk_fma_f32 v[16:17], v[16:17], v[18:19], v[26:27]
	v_pk_fma_f32 v[18:19], v[36:37], v[24:25], v[46:47] neg_lo:[0,0,1] neg_hi:[0,0,1]
	v_pk_fma_f32 v[10:11], v[10:11], v[24:25], v[30:31]
	v_pk_fma_f32 v[20:21], v[38:39], v[28:29], v[48:49] neg_lo:[0,0,1] neg_hi:[0,0,1]
	v_pk_fma_f32 v[12:13], v[12:13], v[28:29], v[34:35]
	v_cndmask_b32_e64 v1, -v15, v7, vcc
	v_cndmask_b32_e64 v4, -v14, v6, vcc
	v_cndmask_b32_e64 v7, -v17, v9, vcc
	v_cndmask_b32_e64 v8, -v16, v8, vcc
	v_cndmask_b32_e64 v9, -v11, v19, vcc
	v_cndmask_b32_e64 v10, -v10, v18, vcc
	v_cndmask_b32_e64 v11, -v13, v21, vcc
	v_cndmask_b32_e64 v12, -v12, v20, vcc
	v_cvt_pk_bf16_f32 v6, v4, v1
	v_cvt_pk_bf16_f32 v7, v8, v7
	v_cvt_pk_bf16_f32 v8, v10, v9
	v_cvt_pk_bf16_f32 v9, v12, v11
	global_store_dwordx4 v[2:3], v[6:9], off
	v_lshl_add_u64 v[2:3], v[2:3], 0, s[8:9]
	v_ashrrev_i32_e32 v1, 14, v0
	v_bfe_u32 v4, v0, 4, 4
	v_lshl_or_b32 v8, v1, 4, v4
	v_mul_i32_i24_e32 v10, 0x41, v1
	v_bfe_u32 v6, v0, 8, 6
	v_mov_b32_e32 v7, v5
	v_ashrrev_i32_e32 v9, 31, v8
	v_ashrrev_i32_e32 v11, 31, v10
	v_and_b32_e32 v12, 56, v22
	v_lshlrev_b64 v[8:9], 8, v[8:9]
	v_lshl_add_u64 v[6:7], v[10:11], 0, v[6:7]
	v_lshlrev_b32_e32 v4, 2, v12
	v_lshl_add_u64 v[10:11], s[38:39], 0, v[8:9]
	v_lshl_add_u64 v[8:9], s[40:41], 0, v[8:9]
	v_lshlrev_b64 v[6:7], 9, v[6:7]
	v_lshl_add_u64 v[36:37], v[10:11], 0, v[4:5]
	v_lshl_add_u64 v[14:15], v[8:9], 0, v[4:5]
	v_lshl_add_u64 v[6:7], s[4:5], 0, v[6:7]
	v_lshlrev_b32_e32 v4, 3, v12
	v_lshl_add_u64 v[32:33], v[6:7], 0, v[4:5]
	global_load_dwordx4 v[164:167], v[36:37], off
	global_load_dwordx4 v[168:171], v[14:15], off offset:16
	s_nop 0
	global_load_dwordx4 v[172:175], v[14:15], off
	s_nop 0
	global_load_dwordx4 v[176:179], v[32:33], off offset:512
	global_load_dwordx4 v[180:183], v[32:33], off offset:528
	global_load_dwordx4 v[184:187], v[32:33], off offset:544
	s_nop 0
	global_load_dwordx4 v[188:191], v[32:33], off offset:560
	s_nop 0
	global_load_dwordx4 v[192:195], v[36:37], off offset:16
	v_and_b32_e32 v237, 8, v0
	v_add_u32_e32 v0, s0, v0
	v_add_u32_e32 v22, s1, v22
	s_waitcnt vmcnt(18)
; DI unsigned pk2(float lo, float hi) { f32x2_t v = {lo, hi}; bf16x2_t b = __builtin_convertvector(v, bf16x2_t); return __builtin_bit_cast(unsigned, b); }
; DI void s5_tables_late(const Params& p, const int gtid, const int gstr) {
;     ...
;     for (int idx = gtid; idx < 32 * 1024 * 16; idx += gstr) {
;         const int g = idx >> 14, m = (idx >> 4) & 1023, kk0 = (idx & 15) * 8;
;         const int t = m >> 4, c = m & 15, p0 = kk0 & 63;
;         const float4* crp = (const float4*)(cre + (size_t)(g * 16 + c) * 64 + p0);
;         const float4* cip = (const float4*)(cim + (size_t)(g * 16 + c) * 64 + p0);
;         float4 cr0 = crp[0], cr1 = crp[1], ci0 = cip[0], ci1 = cip[1];
;         const float crv[8] = {cr0.x, cr0.y, cr0.z, cr0.w, cr1.x, cr1.y, cr1.z, cr1.w};
;         const float civ[8] = {ci0.x, ci0.y, ci0.z, ci0.w, ci1.x, ci1.y, ci1.z, ci1.w};
;         float o[8];
; #pragma unroll
;         for (int e = 0; e < 8; ++e) {
;             const float2 a = apow[((size_t)g * 65 + t + 1) * 64 + p0 + e];
;             o[e] = (kk0 < 64) ? (crv[e] * a.x - civ[e] * a.y) : -(crv[e] * a.y + civ[e] * a.x);
;         }
;         *(uint4*)(cmat + (size_t)idx * 8) = make_uint4(pk2(o[0], o[1]), pk2(o[2], o[3]), pk2(o[4], o[5]), pk2(o[6], o[7]));
	v_mov_b64_e32 v[6:7], v[196:197]
	v_mov_b64_e32 v[8:9], v[198:199]
	v_mov_b64_e32 v[10:11], v[200:201]
	v_mov_b64_e32 v[12:13], v[202:203]
	v_mov_b64_e32 v[14:15], v[204:205]
	v_mov_b64_e32 v[16:17], v[206:207]
	v_mov_b64_e32 v[18:19], v[208:209]
	v_mov_b64_e32 v[20:21], v[210:211]
	v_mov_b64_e32 v[24:25], v[212:213]
	v_mov_b64_e32 v[26:27], v[214:215]
	v_mov_b64_e32 v[28:29], v[216:217]
	v_mov_b64_e32 v[30:31], v[218:219]
	v_mov_b64_e32 v[32:33], v[220:221]
	v_mov_b64_e32 v[34:35], v[222:223]
	v_mov_b64_e32 v[36:37], v[224:225]
	v_mov_b64_e32 v[38:39], v[226:227]
	v_cmp_eq_u32_e32 vcc, 0, v235
	s_nop 1
	v_mov_b32_e32 v41, v20
	v_mov_b32_e32 v20, v19
	v_mov_b32_e32 v19, v26
	v_mov_b32_e32 v26, v25
	v_mov_b32_e32 v25, v30
	v_mov_b32_e32 v30, v29
	v_mov_b32_e32 v29, v34
	v_mov_b32_e32 v34, v33
	v_mov_b32_e32 v40, v18
	v_mov_b32_e32 v18, v24
	v_mov_b32_e32 v24, v28
	v_mov_b32_e32 v28, v32
	v_pk_mul_f32 v[32:33], v[14:15], v[20:21]
	v_pk_mul_f32 v[20:21], v[6:7], v[20:21]
	v_pk_mul_f32 v[42:43], v[16:17], v[26:27]
	v_pk_mul_f32 v[26:27], v[8:9], v[26:27]
	v_pk_mul_f32 v[46:47], v[10:11], v[30:31]
	v_pk_mul_f32 v[30:31], v[36:37], v[30:31]
	v_pk_mul_f32 v[48:49], v[12:13], v[34:35]
	v_pk_mul_f32 v[34:35], v[38:39], v[34:35]
	v_pk_fma_f32 v[6:7], v[6:7], v[40:41], v[32:33] neg_lo:[0,0,1] neg_hi:[0,0,1]
	v_pk_fma_f32 v[14:15], v[14:15], v[40:41], v[20:21]
	v_pk_fma_f32 v[8:9], v[8:9], v[18:19], v[42:43] neg_lo:[0,0,1] neg_hi:[0,0,1]
	v_pk_fma_f32 v[16:17], v[16:17], v[18:19], v[26:27]
	v_pk_fma_f32 v[18:19], v[36:37], v[24:25], v[46:47] neg_lo:[0,0,1] neg_hi:[0,0,1]
	v_pk_fma_f32 v[10:11], v[10:11], v[24:25], v[30:31]
	v_pk_fma_f32 v[20:21], v[38:39], v[28:29], v[48:49] neg_lo:[0,0,1] neg_hi:[0,0,1]
	v_pk_fma_f32 v[12:13], v[12:13], v[28:29], v[34:35]
	v_cndmask_b32_e64 v1, -v15, v7, vcc
	v_cndmask_b32_e64 v4, -v14, v6, vcc
	v_cndmask_b32_e64 v7, -v17, v9, vcc
	v_cndmask_b32_e64 v8, -v16, v8, vcc
	v_cndmask_b32_e64 v9, -v11, v19, vcc
	v_cndmask_b32_e64 v10, -v10, v18, vcc
	v_cndmask_b32_e64 v11, -v13, v21, vcc
	v_cndmask_b32_e64 v12, -v12, v20, vcc
	v_cvt_pk_bf16_f32 v6, v4, v1
	v_cvt_pk_bf16_f32 v7, v8, v7
	v_cvt_pk_bf16_f32 v8, v10, v9
	v_cvt_pk_bf16_f32 v9, v12, v11
	global_store_dwordx4 v[2:3], v[6:9], off
	v_lshl_add_u64 v[2:3], v[2:3], 0, s[8:9]
	s_waitcnt vmcnt(10)
	v_mov_b64_e32 v[6:7], v[128:129]
	v_mov_b64_e32 v[8:9], v[130:131]
	v_mov_b64_e32 v[10:11], v[132:133]
	v_mov_b64_e32 v[12:13], v[134:135]
	v_mov_b64_e32 v[14:15], v[136:137]
	v_mov_b64_e32 v[16:17], v[138:139]
	v_mov_b64_e32 v[18:19], v[140:141]
	v_mov_b64_e32 v[20:21], v[142:143]
	v_mov_b64_e32 v[24:25], v[144:145]
	v_mov_b64_e32 v[26:27], v[146:147]
	v_mov_b64_e32 v[28:29], v[148:149]
	v_mov_b64_e32 v[30:31], v[150:151]
	v_mov_b64_e32 v[32:33], v[152:153]
	v_mov_b64_e32 v[34:35], v[154:155]
	v_mov_b64_e32 v[36:37], v[156:157]
	v_mov_b64_e32 v[38:39], v[158:159]
	v_cmp_eq_u32_e32 vcc, 0, v236
	s_nop 1
	v_mov_b32_e32 v41, v20
	v_mov_b32_e32 v20, v19
	v_mov_b32_e32 v19, v26
	v_mov_b32_e32 v26, v25
	v_mov_b32_e32 v25, v30
	v_mov_b32_e32 v30, v29
	v_mov_b32_e32 v29, v34
	v_mov_b32_e32 v34, v33
	v_mov_b32_e32 v40, v18
	v_mov_b32_e32 v18, v24
	v_mov_b32_e32 v24, v28
	v_mov_b32_e32 v28, v32
	v_pk_mul_f32 v[32:33], v[14:15], v[20:21]
	v_pk_mul_f32 v[20:21], v[6:7], v[20:21]
	v_pk_mul_f32 v[42:43], v[16:17], v[26:27]
	v_pk_mul_f32 v[26:27], v[8:9], v[26:27]
	v_pk_mul_f32 v[46:47], v[10:11], v[30:31]
	v_pk_mul_f32 v[30:31], v[36:37], v[30:31]
	v_pk_mul_f32 v[48:49], v[12:13], v[34:35]
	v_pk_mul_f32 v[34:35], v[38:39], v[34:35]
	v_pk_fma_f32 v[6:7], v[6:7], v[40:41], v[32:33] neg_lo:[0,0,1] neg_hi:[0,0,1]
	v_pk_fma_f32 v[14:15], v[14:15], v[40:41], v[20:21]
	v_pk_fma_f32 v[8:9], v[8:9], v[18:19], v[42:43] neg_lo:[0,0,1] neg_hi:[0,0,1]
	v_pk_fma_f32 v[16:17], v[16:17], v[18:19], v[26:27]
	v_pk_fma_f32 v[18:19], v[36:37], v[24:25], v[46:47] neg_lo:[0,0,1] neg_hi:[0,0,1]
	v_pk_fma_f32 v[10:11], v[10:11], v[24:25], v[30:31]
	v_pk_fma_f32 v[20:21], v[38:39], v[28:29], v[48:49] neg_lo:[0,0,1] neg_hi:[0,0,1]
	v_pk_fma_f32 v[12:13], v[12:13], v[28:29], v[34:35]
	v_cndmask_b32_e64 v1, -v15, v7, vcc
	v_cndmask_b32_e64 v4, -v14, v6, vcc
	v_cndmask_b32_e64 v7, -v17, v9, vcc
	v_cndmask_b32_e64 v8, -v16, v8, vcc
	v_cndmask_b32_e64 v9, -v11, v19, vcc
	v_cndmask_b32_e64 v10, -v10, v18, vcc
	v_cndmask_b32_e64 v11, -v13, v21, vcc
	v_cndmask_b32_e64 v12, -v12, v20, vcc
	v_cvt_pk_bf16_f32 v6, v4, v1
	v_cvt_pk_bf16_f32 v7, v8, v7
	v_cvt_pk_bf16_f32 v8, v10, v9
	v_cvt_pk_bf16_f32 v9, v12, v11
	global_store_dwordx4 v[2:3], v[6:9], off
	v_lshl_add_u64 v[2:3], v[2:3], 0, s[8:9]
	s_waitcnt vmcnt(2)
	v_mov_b64_e32 v[6:7], v[164:165]
	v_mov_b64_e32 v[8:9], v[166:167]
	v_mov_b64_e32 v[10:11], v[168:169]
	v_mov_b64_e32 v[12:13], v[170:171]
	v_mov_b64_e32 v[14:15], v[172:173]
	v_mov_b64_e32 v[16:17], v[174:175]
	v_mov_b64_e32 v[18:19], v[176:177]
	v_mov_b64_e32 v[20:21], v[178:179]
	v_mov_b64_e32 v[24:25], v[180:181]
	v_mov_b64_e32 v[26:27], v[182:183]
	v_mov_b64_e32 v[28:29], v[184:185]
	v_mov_b64_e32 v[30:31], v[186:187]
	v_mov_b64_e32 v[32:33], v[188:189]
	v_mov_b64_e32 v[34:35], v[190:191]
	v_mov_b64_e32 v[36:37], v[192:193]
	v_mov_b64_e32 v[38:39], v[194:195]
	v_cmp_eq_u32_e32 vcc, 0, v237
	s_nop 1
	v_mov_b32_e32 v41, v20
	v_mov_b32_e32 v20, v19
	v_mov_b32_e32 v19, v26
	v_mov_b32_e32 v26, v25
	v_mov_b32_e32 v25, v30
	v_mov_b32_e32 v30, v29
	v_mov_b32_e32 v29, v34
	v_mov_b32_e32 v34, v33
	v_mov_b32_e32 v40, v18
	v_mov_b32_e32 v18, v24
	v_mov_b32_e32 v24, v28
	v_mov_b32_e32 v28, v32
	v_pk_mul_f32 v[32:33], v[14:15], v[20:21]
	v_pk_mul_f32 v[20:21], v[6:7], v[20:21]
	v_pk_mul_f32 v[42:43], v[16:17], v[26:27]
	v_pk_mul_f32 v[26:27], v[8:9], v[26:27]
	v_pk_mul_f32 v[46:47], v[10:11], v[30:31]
	v_pk_mul_f32 v[30:31], v[36:37], v[30:31]
	v_pk_mul_f32 v[48:49], v[12:13], v[34:35]
	v_pk_mul_f32 v[34:35], v[38:39], v[34:35]
	v_pk_fma_f32 v[6:7], v[6:7], v[40:41], v[32:33] neg_lo:[0,0,1] neg_hi:[0,0,1]
	v_pk_fma_f32 v[14:15], v[14:15], v[40:41], v[20:21]
	v_pk_fma_f32 v[8:9], v[8:9], v[18:19], v[42:43] neg_lo:[0,0,1] neg_hi:[0,0,1]
	v_pk_fma_f32 v[16:17], v[16:17], v[18:19], v[26:27]
	v_pk_fma_f32 v[18:19], v[36:37], v[24:25], v[46:47] neg_lo:[0,0,1] neg_hi:[0,0,1]
	v_pk_fma_f32 v[10:11], v[10:11], v[24:25], v[30:31]
	v_pk_fma_f32 v[20:21], v[38:39], v[28:29], v[48:49] neg_lo:[0,0,1] neg_hi:[0,0,1]
	v_pk_fma_f32 v[12:13], v[12:13], v[28:29], v[34:35]
	v_cndmask_b32_e64 v1, -v15, v7, vcc
	v_cndmask_b32_e64 v4, -v14, v6, vcc
	v_cndmask_b32_e64 v7, -v17, v9, vcc
	v_cndmask_b32_e64 v8, -v16, v8, vcc
	v_cndmask_b32_e64 v9, -v11, v19, vcc
	v_cndmask_b32_e64 v10, -v10, v18, vcc
	v_cndmask_b32_e64 v11, -v13, v21, vcc
	v_cndmask_b32_e64 v12, -v12, v20, vcc
	v_cvt_pk_bf16_f32 v6, v4, v1
	v_cvt_pk_bf16_f32 v7, v8, v7
	v_cvt_pk_bf16_f32 v8, v10, v9
	v_cvt_pk_bf16_f32 v9, v12, v11
	global_store_dwordx4 v[2:3], v[6:9], off
	v_lshl_add_u64 v[2:3], v[2:3], 0, s[8:9]
